# RWKV solve LDS-operand prefetch + A1: rows/conv weights preloaded per item + A1 items of one 64-token line group mapped to one XCD
# speedup vs baseline: 1.0116x; 1.0116x over previous
; __device__ __forceinline__ void phase_a1(const P& p, const Ctx& c, int seg) {
;     ...
;     if (n < 384) {
; #pragma unroll
;         for (int i = 0; i < 4; ++i) { const f32x4 a = *(const f32x4*)(p.ml_wq + n * 16 + i * 4), bb = *(const f32x4*)(p.ml_wk + n * 16 + i * 4), cc = *(const f32x4*)(p.ml_wv + n * 16 + i * 4);
; #pragma unroll
;             for (int o = 0; o < 4; ++o) { wq[i][o] = a[o]; wk[i][o] = bb[o]; wv[i][o] = cc[o]; } }
; #pragma unroll
;         for (int i = 0; i < 4; ++i)
; #pragma unroll
;             for (int g = 0; g < 8; ++g) { G12[i][g] = 0.f; G3[i][g] = 0.f; }
; #pragma unroll
;         for (int o = 0; o < 4; ++o) {
;             const float* gq = p.ml_w_gate + (size_t)(n * 4 + o) * 8; const float* gk = p.ml_w_gate + (size_t)(DMIX + n * 4 + o) * 8; const float* gv = p.ml_w_gate + (size_t)(2 * DMIX + n * 4 + o) * 8;
;             const f32x4 q0 = *(const f32x4*)gq, q1 = *(const f32x4*)(gq + 4), k0 = *(const f32x4*)gk, k1 = *(const f32x4*)(gk + 4), v0 = *(const f32x4*)gv, v1 = *(const f32x4*)(gv + 4);
; #pragma unroll
;             for (int i = 0; i < 4; ++i)
; #pragma unroll
;                 for (int g = 0; g < 4; ++g) { G12[i][g] += wq[i][o] * q0[g] + wk[i][o] * k0[g]; G12[i][g + 4] += wq[i][o] * q1[g] + wk[i][o] * k1[g];
;                     G3[i][g] += wv[i][o] * v0[g]; G3[i][g + 4] += wv[i][o] * v1[g]; }
;         }
;     }
; #pragma unroll 1
;     for (int it = c.bid; it < MS / 8; it += c.G) {
.LBB0_240:
	v_mov_b32_e32 v170, v217
	v_readlane_b32 s99, v255, 2
	s_mov_b32 s45, s90
	s_cmp_lg_u32 s99, 0x100
	s_cbranch_scc1 .La1_noperm
	s_and_b32 s45, s90, 7
	s_lshl_b32 s45, s45, 5
	s_lshr_b32 s98, s90, 3
	s_or_b32 s45, s45, s98
.La1_noperm:
	s_mov_b64 s[2:3], s[92:93]
	s_load_dwordx8 s[20:27], s[2:3], 0x38
	s_load_dwordx4 s[4:7], s[2:3], 0x58
	s_load_dwordx2 s[8:9], s[2:3], 0x68
	s_movk_i32 s2, 0x180
	s_mov_b64 s[10:11], 0
	v_cmp_gt_i32_e64 s[2:3], s2, v170
	v_lshlrev_b32_e32 v204, 4, v170
	v_lshlrev_b32_e32 v2, 2, v170
	s_and_saveexec_b64 s[12:13], s[2:3]
	s_cbranch_execz .LBB0_242
	v_ashrrev_i32_e32 v205, 31, v204
	v_ashrrev_i32_e32 v3, 31, v2
	v_lshlrev_b64 v[6:7], 2, v[204:205]
	v_lshlrev_b64 v[18:19], 5, v[2:3]
	s_waitcnt lgkmcnt(0)
	v_lshl_add_u64 v[38:39], s[4:5], 0, v[6:7]
	v_lshl_add_u64 v[18:19], s[6:7], 0, v[18:19]
	s_mov_b64 s[4:5], 0xc000
	v_lshl_add_u64 v[20:21], v[18:19], 0, s[4:5]
	s_mov_b32 s4, 0xc000
	v_lshl_add_u64 v[22:23], s[24:25], 0, v[6:7]
	v_add_co_u32_e32 v24, vcc, s4, v18
	s_mov_b64 s[4:5], 0xc040
	v_lshl_add_u64 v[30:31], s[26:27], 0, v[6:7]
	global_load_dwordx4 v[6:9], v[22:23], off
	global_load_dwordx4 v[10:13], v[30:31], off
	global_load_dwordx4 v[14:17], v[38:39], off
	global_load_dwordx4 v[54:57], v[18:19], off offset:48
	global_load_dwordx4 v[62:65], v[18:19], off offset:32
	global_load_dwordx4 v[70:73], v[18:19], off
	v_addc_co_u32_e32 v25, vcc, 0, v19, vcc
	global_load_dwordx4 v[58:61], v[20:21], off offset:48
	global_load_dwordx4 v[66:69], v[20:21], off offset:16
	global_load_dwordx4 v[74:77], v[20:21], off offset:32
	v_lshl_add_u64 v[20:21], v[18:19], 0, s[4:5]
	s_mov_b32 s4, 0x18000
	global_load_dwordx4 v[90:93], v[24:25], off
	global_load_dwordx4 v[94:97], v[24:25], off offset:64
	global_load_dwordx4 v[82:85], v[20:21], off offset:16
	global_load_dwordx4 v[98:101], v[20:21], off offset:32
	v_add_co_u32_e32 v24, vcc, s4, v18
	v_or_b32_e32 v26, 2, v2
	s_nop 0
	v_addc_co_u32_e32 v25, vcc, 0, v19, vcc
	v_ashrrev_i32_e32 v27, 31, v26
	global_load_dwordx4 v[78:81], v[24:25], off
	global_load_dwordx4 v[86:89], v[20:21], off offset:48
	v_lshlrev_b64 v[20:21], 5, v[26:27]
	v_lshl_add_u64 v[20:21], s[6:7], 0, v[20:21]
	global_load_dwordx4 v[126:129], v[20:21], off
	global_load_dwordx4 v[118:121], v[20:21], off offset:32
	global_load_dwordx4 v[122:125], v[18:19], off offset:16
	global_load_dwordx4 v[102:105], v[20:21], off offset:48
	global_load_dwordx4 v[114:117], v[20:21], off offset:16
	s_mov_b64 s[4:5], 0x18000
	v_lshl_add_u64 v[20:21], v[18:19], 0, s[4:5]
	s_mov_b64 s[4:5], 0x18040
	v_lshl_add_u64 v[18:19], v[18:19], 0, s[4:5]
	global_load_dwordx4 v[106:109], v[20:21], off offset:32
	global_load_dwordx4 v[110:113], v[24:25], off offset:64
	global_load_dwordx4 v[146:149], v[18:19], off offset:32
	global_load_dwordx4 v[134:137], v[20:21], off offset:16
	global_load_dwordx4 v[130:133], v[20:21], off offset:48
	global_load_dwordx4 v[142:145], v[18:19], off offset:16
	global_load_dwordx4 v[138:141], v[18:19], off offset:48
	global_load_dwordx4 v[46:49], v[30:31], off offset:16
	global_load_dwordx4 v[50:53], v[22:23], off offset:16
	global_load_dwordx4 v[42:45], v[38:39], off offset:16
	s_nop 0
	global_load_dwordx4 v[18:21], v[22:23], off offset:48
	s_nop 0
	global_load_dwordx4 v[22:25], v[22:23], off offset:32
	s_nop 0
	global_load_dwordx4 v[26:29], v[30:31], off offset:48
	s_nop 0
	global_load_dwordx4 v[30:33], v[30:31], off offset:32
	s_nop 0
	global_load_dwordx4 v[34:37], v[38:39], off offset:48
	s_nop 0
	global_load_dwordx4 v[38:41], v[38:39], off offset:32
	s_waitcnt vmcnt(35)
	v_mov_b32_e32 v4, v9
	s_waitcnt vmcnt(34)
	v_mov_b32_e32 v160, v13
	s_waitcnt vmcnt(33)
	v_mov_b32_e32 v162, v17
	s_waitcnt vmcnt(29)
	v_pk_mul_f32 v[164:165], v[10:11], v[58:59] op_sel:[1,0]
	s_waitcnt vmcnt(28)
	v_pk_mul_f32 v[158:159], v[10:11], v[66:67] op_sel_hi:[0,1]
	s_waitcnt vmcnt(26)
	v_pk_mul_f32 v[150:151], v[10:11], v[90:91] op_sel_hi:[0,1]
	v_pk_mul_f32 v[152:153], v[10:11], v[74:75] op_sel:[1,0]
	v_pk_fma_f32 v[150:151], v[6:7], v[70:71], v[150:151] op_sel_hi:[0,1,1]
	s_waitcnt vmcnt(25)
	v_pk_mul_f32 v[154:155], v[12:13], v[94:95] op_sel_hi:[0,1]
	v_pk_fma_f32 v[152:153], v[6:7], v[62:63], v[152:153] op_sel:[1,0,0]
	v_pk_add_f32 v[150:151], v[150:151], 0 op_sel_hi:[1,0]
	s_waitcnt vmcnt(23)
	v_pk_mul_f32 v[156:157], v[160:161], v[98:99] op_sel_hi:[0,1]
	v_pk_mul_f32 v[166:167], v[12:13], v[82:83] op_sel_hi:[0,1]
	v_pk_fma_f32 v[164:165], v[6:7], v[54:55], v[164:165] op_sel:[1,0,0]
	v_pk_add_f32 v[150:151], v[150:151], v[152:153]
	s_waitcnt vmcnt(20)
	v_pk_fma_f32 v[154:155], v[8:9], v[126:127], v[154:155] op_sel_hi:[0,1,1]
	s_waitcnt vmcnt(19)
	v_pk_fma_f32 v[156:157], v[4:5], v[118:119], v[156:157] op_sel_hi:[0,1,1]
	s_waitcnt vmcnt(18)
	v_pk_fma_f32 v[158:159], v[6:7], v[122:123], v[158:159] op_sel_hi:[0,1,1]
	v_pk_add_f32 v[158:159], v[158:159], 0 op_sel_hi:[1,0]
	s_waitcnt vmcnt(16)
	v_pk_fma_f32 v[166:167], v[8:9], v[114:115], v[166:167] op_sel_hi:[0,1,1]
	v_pk_add_f32 v[152:153], v[158:159], v[164:165]
	v_pk_add_f32 v[150:151], v[150:151], v[154:155]
	v_pk_add_f32 v[154:155], v[152:153], v[166:167]
	v_pk_add_f32 v[152:153], v[150:151], v[156:157]
	s_waitcnt vmcnt(12)
	v_pk_fma_f32 v[156:157], v[14:15], v[134:135], 0 op_sel_hi:[0,1,0]
	s_waitcnt vmcnt(11)
	v_pk_fma_f32 v[156:157], v[14:15], v[130:131], v[156:157] op_sel:[1,0,0]
	v_pk_mul_f32 v[164:165], v[10:11], v[76:77] op_sel:[1,0]
	s_waitcnt vmcnt(10)
	v_pk_fma_f32 v[156:157], v[16:17], v[142:143], v[156:157] op_sel_hi:[0,1,1]
	s_waitcnt vmcnt(9)
; __device__ __forceinline__ void phase_a1(const P& p, const Ctx& c, int seg) {
;     ...
; #pragma unroll
;         for (int o = 0; o < 4; ++o) {
;             const float* gq = p.ml_w_gate + (size_t)(n * 4 + o) * 8; const float* gk = p.ml_w_gate + (size_t)(DMIX + n * 4 + o) * 8; const float* gv = p.ml_w_gate + (size_t)(2 * DMIX + n * 4 + o) * 8;
;             const f32x4 q0 = *(const f32x4*)gq, q1 = *(const f32x4*)(gq + 4), k0 = *(const f32x4*)gk, k1 = *(const f32x4*)(gk + 4), v0 = *(const f32x4*)gv, v1 = *(const f32x4*)(gv + 4);
; #pragma unroll
;             for (int i = 0; i < 4; ++i)
; #pragma unroll
;                 for (int g = 0; g < 4; ++g) { G12[i][g] += wq[i][o] * q0[g] + wk[i][o] * k0[g]; G12[i][g + 4] += wq[i][o] * q1[g] + wk[i][o] * k1[g];
;                     G3[i][g] += wv[i][o] * v0[g]; G3[i][g + 4] += wv[i][o] * v1[g]; }
;         }
	v_pk_fma_f32 v[158:159], v[162:163], v[138:139], v[156:157] op_sel_hi:[0,1,1]
	v_pk_mul_f32 v[156:157], v[10:11], v[92:93] op_sel_hi:[0,1]
	v_pk_fma_f32 v[156:157], v[6:7], v[72:73], v[156:157] op_sel_hi:[0,1,1]
	v_pk_add_f32 v[156:157], v[156:157], 0 op_sel_hi:[1,0]
	v_pk_fma_f32 v[164:165], v[6:7], v[64:65], v[164:165] op_sel:[1,0,0]
	v_pk_mul_f32 v[166:167], v[10:11], v[60:61] op_sel:[1,0]
	v_pk_add_f32 v[156:157], v[156:157], v[164:165]
	v_pk_mul_f32 v[164:165], v[12:13], v[96:97] op_sel_hi:[0,1]
	v_pk_fma_f32 v[164:165], v[8:9], v[128:129], v[164:165] op_sel_hi:[0,1,1]
	v_pk_add_f32 v[156:157], v[156:157], v[164:165]
	v_pk_mul_f32 v[164:165], v[160:161], v[100:101] op_sel_hi:[0,1]
	v_pk_fma_f32 v[164:165], v[4:5], v[120:121], v[164:165] op_sel_hi:[0,1,1]
	v_pk_add_f32 v[156:157], v[156:157], v[164:165]
	v_pk_mul_f32 v[164:165], v[10:11], v[68:69] op_sel_hi:[0,1]
	v_pk_fma_f32 v[164:165], v[6:7], v[124:125], v[164:165] op_sel_hi:[0,1,1]
	v_pk_add_f32 v[164:165], v[164:165], 0 op_sel_hi:[1,0]
	v_pk_fma_f32 v[166:167], v[6:7], v[56:57], v[166:167] op_sel:[1,0,0]
	v_pk_mul_f32 v[168:169], v[160:161], v[86:87] op_sel_hi:[0,1]
	v_pk_add_f32 v[164:165], v[164:165], v[166:167]
	v_pk_mul_f32 v[166:167], v[12:13], v[84:85] op_sel_hi:[0,1]
	v_pk_fma_f32 v[166:167], v[8:9], v[116:117], v[166:167] op_sel_hi:[0,1,1]
	v_pk_mul_f32 v[160:161], v[160:161], v[88:89] op_sel_hi:[0,1]
	v_pk_add_f32 v[164:165], v[164:165], v[166:167]
	v_pk_fma_f32 v[160:161], v[4:5], v[104:105], v[160:161] op_sel_hi:[0,1,1]
	v_pk_add_f32 v[160:161], v[164:165], v[160:161]
	v_pk_fma_f32 v[164:165], v[14:15], v[80:81], 0 op_sel_hi:[0,1,0]
	v_pk_fma_f32 v[164:165], v[14:15], v[108:109], v[164:165] op_sel:[1,0,0]
	v_pk_fma_f32 v[172:173], v[14:15], v[78:79], 0 op_sel_hi:[0,1,0]
	v_pk_fma_f32 v[164:165], v[16:17], v[112:113], v[164:165] op_sel_hi:[0,1,1]
	v_pk_fma_f32 v[166:167], v[162:163], v[148:149], v[164:165] op_sel_hi:[0,1,1]
	v_pk_fma_f32 v[164:165], v[14:15], v[136:137], 0 op_sel_hi:[0,1,0]
	v_pk_fma_f32 v[172:173], v[14:15], v[106:107], v[172:173] op_sel:[1,0,0]
	v_pk_fma_f32 v[164:165], v[14:15], v[132:133], v[164:165] op_sel:[1,0,0]
	v_pk_fma_f32 v[168:169], v[4:5], v[102:103], v[168:169] op_sel_hi:[0,1,1]
	v_pk_fma_f32 v[172:173], v[16:17], v[110:111], v[172:173] op_sel_hi:[0,1,1]
	v_pk_fma_f32 v[164:165], v[16:17], v[144:145], v[164:165] op_sel_hi:[0,1,1]
	v_pk_add_f32 v[150:151], v[154:155], v[168:169]
	v_pk_fma_f32 v[154:155], v[162:163], v[146:147], v[172:173] op_sel_hi:[0,1,1]
	v_pk_fma_f32 v[168:169], v[162:163], v[140:141], v[164:165] op_sel_hi:[0,1,1]
	s_waitcnt vmcnt(8)
	v_pk_mul_f32 v[162:163], v[46:47], v[90:91] op_sel_hi:[0,1]
	s_waitcnt vmcnt(7)
	v_pk_fma_f32 v[162:163], v[50:51], v[70:71], v[162:163] op_sel_hi:[0,1,1]
	v_pk_mul_f32 v[164:165], v[46:47], v[74:75] op_sel:[1,0]
	v_pk_add_f32 v[162:163], v[162:163], 0 op_sel_hi:[1,0]
	v_pk_fma_f32 v[164:165], v[50:51], v[62:63], v[164:165] op_sel:[1,0,0]
	v_mov_b32_e32 v172, v49
	v_pk_add_f32 v[162:163], v[162:163], v[164:165]
	v_pk_mul_f32 v[164:165], v[48:49], v[94:95] op_sel_hi:[0,1]
	v_pk_fma_f32 v[164:165], v[52:53], v[126:127], v[164:165] op_sel_hi:[0,1,1]
	v_pk_add_f32 v[162:163], v[162:163], v[164:165]
	v_mov_b32_e32 v4, v53
	v_pk_mul_f32 v[164:165], v[172:173], v[98:99] op_sel_hi:[0,1]
	v_pk_fma_f32 v[164:165], v[4:5], v[118:119], v[164:165] op_sel_hi:[0,1,1]
	v_pk_add_f32 v[162:163], v[162:163], v[164:165]
	v_pk_mul_f32 v[164:165], v[46:47], v[66:67] op_sel_hi:[0,1]
	v_pk_fma_f32 v[164:165], v[50:51], v[122:123], v[164:165] op_sel_hi:[0,1,1]
	v_pk_mul_f32 v[176:177], v[46:47], v[58:59] op_sel:[1,0]
	v_pk_add_f32 v[164:165], v[164:165], 0 op_sel_hi:[1,0]
	v_pk_fma_f32 v[176:177], v[50:51], v[54:55], v[176:177] op_sel:[1,0,0]
	s_waitcnt vmcnt(6)
	v_mov_b32_e32 v174, v45
	v_pk_add_f32 v[164:165], v[164:165], v[176:177]
	v_pk_mul_f32 v[176:177], v[48:49], v[82:83] op_sel_hi:[0,1]
	v_pk_fma_f32 v[176:177], v[52:53], v[114:115], v[176:177] op_sel_hi:[0,1,1]
	v_pk_add_f32 v[164:165], v[164:165], v[176:177]
	v_pk_mul_f32 v[176:177], v[172:173], v[86:87] op_sel_hi:[0,1]
	v_pk_fma_f32 v[176:177], v[4:5], v[102:103], v[176:177] op_sel_hi:[0,1,1]
	v_pk_add_f32 v[164:165], v[164:165], v[176:177]
	v_pk_fma_f32 v[176:177], v[42:43], v[78:79], 0 op_sel_hi:[0,1,0]
	v_pk_fma_f32 v[176:177], v[42:43], v[106:107], v[176:177] op_sel:[1,0,0]
	v_pk_mul_f32 v[178:179], v[46:47], v[76:77] op_sel:[1,0]
	v_pk_fma_f32 v[176:177], v[44:45], v[110:111], v[176:177] op_sel_hi:[0,1,1]
	v_pk_fma_f32 v[182:183], v[174:175], v[146:147], v[176:177] op_sel_hi:[0,1,1]
	v_pk_fma_f32 v[176:177], v[42:43], v[134:135], 0 op_sel_hi:[0,1,0]
	v_pk_fma_f32 v[176:177], v[42:43], v[130:131], v[176:177] op_sel:[1,0,0]
	v_pk_fma_f32 v[178:179], v[50:51], v[64:65], v[178:179] op_sel:[1,0,0]
	v_pk_fma_f32 v[176:177], v[44:45], v[142:143], v[176:177] op_sel_hi:[0,1,1]
	v_pk_fma_f32 v[180:181], v[174:175], v[138:139], v[176:177] op_sel_hi:[0,1,1]
	v_pk_mul_f32 v[176:177], v[46:47], v[92:93] op_sel_hi:[0,1]
	v_pk_fma_f32 v[176:177], v[50:51], v[72:73], v[176:177] op_sel_hi:[0,1,1]
	v_pk_add_f32 v[176:177], v[176:177], 0 op_sel_hi:[1,0]
	v_pk_mul_f32 v[184:185], v[46:47], v[60:61] op_sel:[1,0]
	v_pk_add_f32 v[176:177], v[176:177], v[178:179]
	v_pk_mul_f32 v[178:179], v[48:49], v[96:97] op_sel_hi:[0,1]
	v_pk_fma_f32 v[178:179], v[52:53], v[128:129], v[178:179] op_sel_hi:[0,1,1]
	v_pk_add_f32 v[176:177], v[176:177], v[178:179]
	v_pk_mul_f32 v[178:179], v[172:173], v[100:101] op_sel_hi:[0,1]
	v_pk_fma_f32 v[178:179], v[4:5], v[120:121], v[178:179] op_sel_hi:[0,1,1]
	v_pk_add_f32 v[176:177], v[176:177], v[178:179]
	v_pk_mul_f32 v[178:179], v[46:47], v[68:69] op_sel_hi:[0,1]
	v_pk_fma_f32 v[178:179], v[50:51], v[124:125], v[178:179] op_sel_hi:[0,1,1]
	v_pk_add_f32 v[178:179], v[178:179], 0 op_sel_hi:[1,0]
	v_pk_fma_f32 v[184:185], v[50:51], v[56:57], v[184:185] op_sel:[1,0,0]
	v_pk_mul_f32 v[172:173], v[172:173], v[88:89] op_sel_hi:[0,1]
	v_pk_add_f32 v[178:179], v[178:179], v[184:185]
	v_pk_mul_f32 v[184:185], v[48:49], v[84:85] op_sel_hi:[0,1]
	v_pk_fma_f32 v[184:185], v[52:53], v[116:117], v[184:185] op_sel_hi:[0,1,1]
	v_pk_add_f32 v[178:179], v[178:179], v[184:185]
	v_pk_fma_f32 v[172:173], v[4:5], v[104:105], v[172:173] op_sel_hi:[0,1,1]
	v_pk_add_f32 v[178:179], v[178:179], v[172:173]
	v_pk_fma_f32 v[172:173], v[42:43], v[80:81], 0 op_sel_hi:[0,1,0]
	v_pk_fma_f32 v[172:173], v[42:43], v[108:109], v[172:173] op_sel:[1,0,0]
	s_waitcnt vmcnt(2)
; __device__ __forceinline__ void phase_a1(const P& p, const Ctx& c, int seg) {
;     ...
; #pragma unroll
;         for (int o = 0; o < 4; ++o) {
;             const float* gq = p.ml_w_gate + (size_t)(n * 4 + o) * 8; const float* gk = p.ml_w_gate + (size_t)(DMIX + n * 4 + o) * 8; const float* gv = p.ml_w_gate + (size_t)(2 * DMIX + n * 4 + o) * 8;
;             const f32x4 q0 = *(const f32x4*)gq, q1 = *(const f32x4*)(gq + 4), k0 = *(const f32x4*)gk, k1 = *(const f32x4*)(gk + 4), v0 = *(const f32x4*)gv, v1 = *(const f32x4*)(gv + 4);
; #pragma unroll
;             for (int i = 0; i < 4; ++i)
; #pragma unroll
;                 for (int g = 0; g < 4; ++g) { G12[i][g] += wq[i][o] * q0[g] + wk[i][o] * k0[g]; G12[i][g + 4] += wq[i][o] * q1[g] + wk[i][o] * k1[g];
;                     G3[i][g] += wv[i][o] * v0[g]; G3[i][g + 4] += wv[i][o] * v1[g]; }
;         }
	v_pk_mul_f32 v[184:185], v[30:31], v[74:75] op_sel:[1,0]
	v_pk_fma_f32 v[172:173], v[44:45], v[112:113], v[172:173] op_sel_hi:[0,1,1]
	v_pk_fma_f32 v[190:191], v[174:175], v[148:149], v[172:173] op_sel_hi:[0,1,1]
	v_pk_fma_f32 v[172:173], v[42:43], v[136:137], 0 op_sel_hi:[0,1,0]
	v_pk_fma_f32 v[172:173], v[42:43], v[132:133], v[172:173] op_sel:[1,0,0]
	v_pk_fma_f32 v[184:185], v[22:23], v[62:63], v[184:185] op_sel:[1,0,0]
	v_pk_fma_f32 v[172:173], v[44:45], v[144:145], v[172:173] op_sel_hi:[0,1,1]
	v_pk_fma_f32 v[188:189], v[174:175], v[140:141], v[172:173] op_sel_hi:[0,1,1]
	v_pk_mul_f32 v[172:173], v[30:31], v[90:91] op_sel_hi:[0,1]
	v_pk_fma_f32 v[172:173], v[22:23], v[70:71], v[172:173] op_sel_hi:[0,1,1]
	v_pk_add_f32 v[172:173], v[172:173], 0 op_sel_hi:[1,0]
	v_mov_b32_e32 v174, v33
	v_pk_add_f32 v[172:173], v[172:173], v[184:185]
	v_pk_mul_f32 v[184:185], v[32:33], v[94:95] op_sel_hi:[0,1]
	v_pk_fma_f32 v[184:185], v[24:25], v[126:127], v[184:185] op_sel_hi:[0,1,1]
	v_pk_add_f32 v[172:173], v[172:173], v[184:185]
	v_mov_b32_e32 v4, v25
	v_pk_mul_f32 v[184:185], v[174:175], v[98:99] op_sel_hi:[0,1]
	v_pk_fma_f32 v[184:185], v[4:5], v[118:119], v[184:185] op_sel_hi:[0,1,1]
	v_pk_add_f32 v[184:185], v[172:173], v[184:185]
	v_pk_mul_f32 v[172:173], v[30:31], v[66:67] op_sel_hi:[0,1]
	v_pk_fma_f32 v[172:173], v[22:23], v[122:123], v[172:173] op_sel_hi:[0,1,1]
	v_pk_mul_f32 v[186:187], v[30:31], v[58:59] op_sel:[1,0]
	v_pk_add_f32 v[172:173], v[172:173], 0 op_sel_hi:[1,0]
	v_pk_fma_f32 v[186:187], v[22:23], v[54:55], v[186:187] op_sel:[1,0,0]
	s_waitcnt vmcnt(0)
	v_mov_b32_e32 v202, v41
	v_pk_add_f32 v[172:173], v[172:173], v[186:187]
	v_pk_mul_f32 v[186:187], v[32:33], v[82:83] op_sel_hi:[0,1]
	v_pk_fma_f32 v[186:187], v[24:25], v[114:115], v[186:187] op_sel_hi:[0,1,1]
	v_pk_add_f32 v[172:173], v[172:173], v[186:187]
	v_pk_mul_f32 v[186:187], v[174:175], v[86:87] op_sel_hi:[0,1]
	v_pk_fma_f32 v[186:187], v[4:5], v[102:103], v[186:187] op_sel_hi:[0,1,1]
	v_pk_add_f32 v[186:187], v[172:173], v[186:187]
	v_pk_fma_f32 v[172:173], v[38:39], v[78:79], 0 op_sel_hi:[0,1,0]
	v_pk_fma_f32 v[172:173], v[38:39], v[106:107], v[172:173] op_sel:[1,0,0]
	v_pk_mul_f32 v[192:193], v[30:31], v[76:77] op_sel:[1,0]
	v_pk_fma_f32 v[172:173], v[40:41], v[110:111], v[172:173] op_sel_hi:[0,1,1]
	v_pk_fma_f32 v[196:197], v[202:203], v[146:147], v[172:173] op_sel_hi:[0,1,1]
	v_pk_fma_f32 v[172:173], v[38:39], v[134:135], 0 op_sel_hi:[0,1,0]
	v_pk_fma_f32 v[172:173], v[38:39], v[130:131], v[172:173] op_sel:[1,0,0]
	v_pk_fma_f32 v[192:193], v[22:23], v[64:65], v[192:193] op_sel:[1,0,0]
	v_pk_fma_f32 v[172:173], v[40:41], v[142:143], v[172:173] op_sel_hi:[0,1,1]
	v_pk_fma_f32 v[198:199], v[202:203], v[138:139], v[172:173] op_sel_hi:[0,1,1]
	v_pk_mul_f32 v[172:173], v[30:31], v[92:93] op_sel_hi:[0,1]
	v_pk_fma_f32 v[172:173], v[22:23], v[72:73], v[172:173] op_sel_hi:[0,1,1]
	v_pk_add_f32 v[172:173], v[172:173], 0 op_sel_hi:[1,0]
	v_pk_mul_f32 v[194:195], v[30:31], v[60:61] op_sel:[1,0]
	v_pk_add_f32 v[172:173], v[172:173], v[192:193]
	v_pk_mul_f32 v[192:193], v[32:33], v[96:97] op_sel_hi:[0,1]
	v_pk_fma_f32 v[192:193], v[24:25], v[128:129], v[192:193] op_sel_hi:[0,1,1]
	v_pk_add_f32 v[172:173], v[172:173], v[192:193]
	v_pk_mul_f32 v[192:193], v[174:175], v[100:101] op_sel_hi:[0,1]
	v_pk_fma_f32 v[192:193], v[4:5], v[120:121], v[192:193] op_sel_hi:[0,1,1]
	v_pk_add_f32 v[192:193], v[172:173], v[192:193]
	v_pk_mul_f32 v[172:173], v[30:31], v[68:69] op_sel_hi:[0,1]
	v_pk_fma_f32 v[172:173], v[22:23], v[124:125], v[172:173] op_sel_hi:[0,1,1]
	v_pk_add_f32 v[172:173], v[172:173], 0 op_sel_hi:[1,0]
	v_pk_fma_f32 v[194:195], v[22:23], v[56:57], v[194:195] op_sel:[1,0,0]
	v_pk_mul_f32 v[66:67], v[26:27], v[66:67] op_sel_hi:[0,1]
	v_pk_add_f32 v[172:173], v[172:173], v[194:195]
	v_pk_mul_f32 v[194:195], v[32:33], v[84:85] op_sel_hi:[0,1]
	v_pk_fma_f32 v[66:67], v[18:19], v[122:123], v[66:67] op_sel_hi:[0,1,1]
	v_pk_mul_f32 v[58:59], v[26:27], v[58:59] op_sel:[1,0]
	v_pk_fma_f32 v[194:195], v[24:25], v[116:117], v[194:195] op_sel_hi:[0,1,1]
	v_pk_mul_f32 v[74:75], v[26:27], v[74:75] op_sel:[1,0]
	v_pk_add_f32 v[66:67], v[66:67], 0 op_sel_hi:[1,0]
	v_pk_fma_f32 v[54:55], v[18:19], v[54:55], v[58:59] op_sel:[1,0,0]
	v_pk_mul_f32 v[58:59], v[28:29], v[82:83] op_sel_hi:[0,1]
	v_pk_add_f32 v[172:173], v[172:173], v[194:195]
	v_pk_mul_f32 v[194:195], v[174:175], v[88:89] op_sel_hi:[0,1]
	v_pk_fma_f32 v[62:63], v[18:19], v[62:63], v[74:75] op_sel:[1,0,0]
	v_mov_b32_e32 v74, v29
	v_pk_add_f32 v[54:55], v[66:67], v[54:55]
	v_pk_fma_f32 v[58:59], v[20:21], v[114:115], v[58:59] op_sel_hi:[0,1,1]
	v_pk_fma_f32 v[194:195], v[4:5], v[104:105], v[194:195] op_sel_hi:[0,1,1]
; __device__ __forceinline__ void phase_a1(const P& p, const Ctx& c, int seg) {
;     ...
; #pragma unroll
;         for (int o = 0; o < 4; ++o) {
;             const float* gq = p.ml_w_gate + (size_t)(n * 4 + o) * 8; const float* gk = p.ml_w_gate + (size_t)(DMIX + n * 4 + o) * 8; const float* gv = p.ml_w_gate + (size_t)(2 * DMIX + n * 4 + o) * 8;
;             const f32x4 q0 = *(const f32x4*)gq, q1 = *(const f32x4*)(gq + 4), k0 = *(const f32x4*)gk, k1 = *(const f32x4*)(gk + 4), v0 = *(const f32x4*)gv, v1 = *(const f32x4*)(gv + 4);
; #pragma unroll
;             for (int i = 0; i < 4; ++i)
; #pragma unroll
;                 for (int g = 0; g < 4; ++g) { G12[i][g] += wq[i][o] * q0[g] + wk[i][o] * k0[g]; G12[i][g + 4] += wq[i][o] * q1[g] + wk[i][o] * k1[g];
;                     G3[i][g] += wv[i][o] * v0[g]; G3[i][g + 4] += wv[i][o] * v1[g]; }
;         }
	v_mov_b32_e32 v4, v21
	v_pk_add_f32 v[54:55], v[54:55], v[58:59]
	v_pk_mul_f32 v[58:59], v[74:75], v[86:87] op_sel_hi:[0,1]
	v_pk_mul_f32 v[90:91], v[26:27], v[90:91] op_sel_hi:[0,1]
	v_pk_fma_f32 v[58:59], v[4:5], v[102:103], v[58:59] op_sel_hi:[0,1,1]
	v_pk_fma_f32 v[70:71], v[18:19], v[70:71], v[90:91] op_sel_hi:[0,1,1]
	v_pk_add_f32 v[54:55], v[54:55], v[58:59]
	v_pk_fma_f32 v[58:59], v[34:35], v[78:79], 0 op_sel_hi:[0,1,0]
	v_pk_add_f32 v[70:71], v[70:71], 0 op_sel_hi:[1,0]
	v_pk_fma_f32 v[58:59], v[34:35], v[106:107], v[58:59] op_sel:[1,0,0]
	v_pk_add_f32 v[62:63], v[70:71], v[62:63]
	v_pk_mul_f32 v[70:71], v[28:29], v[94:95] op_sel_hi:[0,1]
	v_pk_fma_f32 v[58:59], v[36:37], v[110:111], v[58:59] op_sel_hi:[0,1,1]
	v_mov_b32_e32 v78, v37
	v_pk_fma_f32 v[70:71], v[20:21], v[126:127], v[70:71] op_sel_hi:[0,1,1]
	v_pk_fma_f32 v[66:67], v[78:79], v[146:147], v[58:59] op_sel_hi:[0,1,1]
	v_pk_fma_f32 v[58:59], v[34:35], v[134:135], 0 op_sel_hi:[0,1,0]
	v_pk_add_f32 v[62:63], v[62:63], v[70:71]
	v_pk_mul_f32 v[70:71], v[74:75], v[98:99] op_sel_hi:[0,1]
	v_pk_fma_f32 v[58:59], v[34:35], v[130:131], v[58:59] op_sel:[1,0,0]
	v_pk_fma_f32 v[70:71], v[4:5], v[118:119], v[70:71] op_sel_hi:[0,1,1]
	v_pk_fma_f32 v[58:59], v[36:37], v[142:143], v[58:59] op_sel_hi:[0,1,1]
	v_pk_add_f32 v[62:63], v[62:63], v[70:71]
	v_pk_fma_f32 v[70:71], v[78:79], v[138:139], v[58:59] op_sel_hi:[0,1,1]
	v_pk_mul_f32 v[58:59], v[26:27], v[92:93] op_sel_hi:[0,1]
	v_pk_fma_f32 v[58:59], v[18:19], v[72:73], v[58:59] op_sel_hi:[0,1,1]
	v_pk_mul_f32 v[72:73], v[26:27], v[76:77] op_sel:[1,0]
	v_pk_add_f32 v[58:59], v[58:59], 0 op_sel_hi:[1,0]
	v_pk_fma_f32 v[64:65], v[18:19], v[64:65], v[72:73] op_sel:[1,0,0]
	v_pk_mul_f32 v[60:61], v[26:27], v[60:61] op_sel:[1,0]
	v_pk_add_f32 v[58:59], v[58:59], v[64:65]
	v_pk_mul_f32 v[64:65], v[28:29], v[96:97] op_sel_hi:[0,1]
	v_pk_fma_f32 v[64:65], v[20:21], v[128:129], v[64:65] op_sel_hi:[0,1,1]
	v_pk_add_f32 v[58:59], v[58:59], v[64:65]
	v_pk_mul_f32 v[64:65], v[74:75], v[100:101] op_sel_hi:[0,1]
	v_pk_fma_f32 v[64:65], v[4:5], v[120:121], v[64:65] op_sel_hi:[0,1,1]
	v_pk_add_f32 v[58:59], v[58:59], v[64:65]
	v_pk_mul_f32 v[64:65], v[26:27], v[68:69] op_sel_hi:[0,1]
	v_pk_fma_f32 v[64:65], v[18:19], v[124:125], v[64:65] op_sel_hi:[0,1,1]
	v_pk_add_f32 v[64:65], v[64:65], 0 op_sel_hi:[1,0]
	v_pk_fma_f32 v[56:57], v[18:19], v[56:57], v[60:61] op_sel:[1,0,0]
	v_pk_mul_f32 v[60:61], v[28:29], v[84:85] op_sel_hi:[0,1]
	v_pk_add_f32 v[56:57], v[64:65], v[56:57]
	v_pk_fma_f32 v[60:61], v[20:21], v[116:117], v[60:61] op_sel_hi:[0,1,1]
	v_pk_add_f32 v[56:57], v[56:57], v[60:61]
	v_pk_mul_f32 v[60:61], v[74:75], v[88:89] op_sel_hi:[0,1]
	v_pk_fma_f32 v[60:61], v[4:5], v[104:105], v[60:61] op_sel_hi:[0,1,1]
	v_pk_add_f32 v[194:195], v[172:173], v[194:195]
	v_pk_fma_f32 v[172:173], v[38:39], v[80:81], 0 op_sel_hi:[0,1,0]
	v_pk_add_f32 v[56:57], v[56:57], v[60:61]
	v_pk_fma_f32 v[60:61], v[34:35], v[80:81], 0 op_sel_hi:[0,1,0]
	v_pk_fma_f32 v[172:173], v[38:39], v[108:109], v[172:173] op_sel:[1,0,0]
	v_pk_fma_f32 v[60:61], v[34:35], v[108:109], v[60:61] op_sel:[1,0,0]
	v_pk_fma_f32 v[172:173], v[40:41], v[112:113], v[172:173] op_sel_hi:[0,1,1]
	v_pk_fma_f32 v[60:61], v[36:37], v[112:113], v[60:61] op_sel_hi:[0,1,1]
	v_pk_fma_f32 v[200:201], v[202:203], v[148:149], v[172:173] op_sel_hi:[0,1,1]
	v_pk_fma_f32 v[172:173], v[38:39], v[136:137], 0 op_sel_hi:[0,1,0]
	v_pk_fma_f32 v[64:65], v[78:79], v[148:149], v[60:61] op_sel_hi:[0,1,1]
	v_pk_fma_f32 v[60:61], v[34:35], v[136:137], 0 op_sel_hi:[0,1,0]
	v_pk_fma_f32 v[172:173], v[38:39], v[132:133], v[172:173] op_sel:[1,0,0]
	v_pk_fma_f32 v[60:61], v[34:35], v[132:133], v[60:61] op_sel:[1,0,0]
	v_pk_fma_f32 v[172:173], v[40:41], v[144:145], v[172:173] op_sel_hi:[0,1,1]
	v_pk_fma_f32 v[60:61], v[36:37], v[144:145], v[60:61] op_sel_hi:[0,1,1]
	v_pk_fma_f32 v[202:203], v[202:203], v[140:141], v[172:173] op_sel_hi:[0,1,1]
	v_pk_fma_f32 v[68:69], v[78:79], v[140:141], v[60:61] op_sel_hi:[0,1,1]
	v_mov_b32_e32 v60, v52
	v_mov_b32_e32 v61, v9
	v_mov_b32_e32 v9, v53
	v_mov_b32_e32 v52, v50
	v_mov_b32_e32 v53, v7
	v_mov_b32_e32 v7, v51
	v_mov_b32_e32 v50, v48
	v_mov_b32_e32 v51, v13
	v_mov_b32_e32 v13, v49
	v_mov_b32_e32 v48, v46
	v_mov_b32_e32 v49, v11
	v_mov_b32_e32 v11, v47
	v_mov_b32_e32 v46, v44
	v_mov_b32_e32 v47, v17
	v_mov_b32_e32 v17, v45
	v_mov_b32_e32 v44, v42
	v_mov_b32_e32 v45, v15
	v_mov_b32_e32 v15, v43
	v_mov_b32_e32 v42, v195
	v_mov_b32_e32 v72, v187
	v_mov_b32_e32 v74, v193
	v_mov_b32_e32 v76, v185
	v_mov_b32_e32 v78, v161
	v_mov_b32_e32 v80, v151
	v_mov_b32_e32 v82, v157
	v_mov_b32_e32 v84, v153
	v_mov_b32_e32 v86, v169
	v_mov_b32_e32 v88, v159
	v_mov_b32_e32 v90, v167
	v_mov_b32_e32 v92, v155
